# baseline (speedup 1.0000x reference)
; __device__ __forceinline__ unsigned xb_ld(unsigned* p)              { return __hip_atomic_load(p, __ATOMIC_RELAXED, __HIP_MEMORY_SCOPE_AGENT); }
; __device__ __forceinline__ void xcd_barrier_complete(unsigned* bar, unsigned x, unsigned& nloc, unsigned& nx) {
;     ...
;     for (;;) {
;         sum = 0u; cnt = 0u; mine = 0u;
; #pragma unroll
;         for (unsigned j = 0; j < 16; ++j) { const unsigned c = xb_ld(&bar[XB_XCNT(j)]); sum += c; cnt += (c > 0u) ? 1u : 0u; mine = (j == x) ? c : mine; }
;         if (sum == G) break;
;         __builtin_amdgcn_s_sleep(1);
;         if ((++sp & 255u) == 0u) { if (xb_ld(&bar[XB_TMO])) break; if (sp > XB_SPIN_CAP) { atomicAdd(&bar[XB_TMO], 1u); break; } }
;     }
.LBB0_347:
	v_readlane_b32 s14, v253, 49
	v_readlane_b32 s15, v253, 50
	s_mov_b64 s[36:37], -1
	s_mov_b64 s[38:39], -1
	s_waitcnt lgkmcnt(0)
	s_nop 1
	global_load_dword v0, v161, s[14:15] sc1
	v_readlane_b32 s14, v253, 51
	v_readlane_b32 s15, v253, 52
	s_nop 4
	global_load_dword v1, v161, s[14:15] sc1
	v_readlane_b32 s14, v253, 53
	v_readlane_b32 s15, v253, 54
	s_nop 0
	s_nop 0
	s_nop 2
	global_load_dword v2, v161, s[14:15] sc1
	v_readlane_b32 s14, v253, 55
	v_readlane_b32 s15, v253, 56
	s_nop 0
	s_nop 0
	s_nop 2
	global_load_dword v3, v161, s[14:15] sc1
	v_readlane_b32 s14, v253, 57
	v_readlane_b32 s15, v253, 58
	s_nop 0
	s_nop 0
	s_nop 2
	global_load_dword v4, v161, s[14:15] sc1
	v_readlane_b32 s14, v253, 59
	v_readlane_b32 s15, v253, 60
	s_nop 0
	s_nop 0
	s_nop 2
	global_load_dword v5, v161, s[14:15] sc1
	v_readlane_b32 s14, v253, 61
	v_readlane_b32 s15, v253, 62
	s_nop 0
	s_nop 0
	s_nop 2
	global_load_dword v6, v161, s[14:15] sc1
	v_readlane_b32 s14, v253, 63
	v_readlane_b32 s15, v255, 0
	s_nop 0
	s_nop 0
	s_nop 2
	global_load_dword v7, v161, s[14:15] sc1
	v_readlane_b32 s14, v255, 1
	v_readlane_b32 s15, v255, 2
	s_nop 0
	s_nop 0
	s_nop 2
	global_load_dword v8, v161, s[14:15] sc1
	v_readlane_b32 s14, v255, 3
	v_readlane_b32 s15, v255, 4
	s_nop 0
	s_nop 0
	s_nop 2
	global_load_dword v9, v161, s[14:15] sc1
	v_readlane_b32 s14, v255, 5
	v_readlane_b32 s15, v255, 6
	s_nop 0
	s_nop 0
	s_nop 2
	global_load_dword v10, v161, s[14:15] sc1
	v_readlane_b32 s14, v255, 7
	v_readlane_b32 s15, v255, 8
	s_nop 0
	s_nop 0
	s_nop 2
	global_load_dword v11, v161, s[14:15] sc1
	v_readlane_b32 s14, v255, 9
	v_readlane_b32 s15, v255, 10
	s_nop 0
	s_nop 0
	s_nop 2
	global_load_dword v12, v161, s[14:15] sc1
	v_readlane_b32 s14, v255, 11
	v_readlane_b32 s15, v255, 12
	s_nop 0
	s_nop 0
	s_nop 2
	global_load_dword v13, v161, s[14:15] sc1
	v_readlane_b32 s14, v255, 13
	v_readlane_b32 s15, v255, 14
	s_nop 0
	s_nop 0
	s_nop 2
	global_load_dword v14, v161, s[14:15] sc1
	v_readlane_b32 s14, v255, 15
	v_readlane_b32 s15, v255, 16
	s_nop 0
	s_nop 0
	s_nop 2
	global_load_dword v15, v161, s[14:15] sc1
	s_waitcnt vmcnt(0)
	v_add_u32_e32 v16, v1, v0
	v_add_u32_e32 v16, v16, v2
	v_add_u32_e32 v16, v16, v3
	v_add_u32_e32 v16, v16, v4
	v_add_u32_e32 v16, v16, v5
	v_add_u32_e32 v16, v16, v6
	v_add_u32_e32 v16, v16, v7
	v_add_u32_e32 v16, v16, v8
	v_add_u32_e32 v16, v16, v9
	v_add_u32_e32 v16, v16, v10
	v_add_u32_e32 v16, v16, v11
	v_add_u32_e32 v16, v16, v12
	v_add_u32_e32 v16, v16, v13
	v_add_u32_e32 v16, v16, v14
	v_add_u32_e32 v16, v16, v15
	v_cmp_eq_u32_e32 vcc, s29, v16
	s_cbranch_vccnz .LBB0_346
	s_and_b32 s14, s7, 0xff
	s_cmp_eq_u32 s14, 0
	s_mov_b64 s[14:15], -1
	s_sleep 1
	s_cbranch_scc1 .LBB0_351
	s_and_b64 vcc, exec, s[14:15]
	s_cbranch_vccz .LBB0_346
